# GDN chunk loop: o read-back of the finished chunk issued with the next chunk's first operand reads (counted lgkmcnt(12)) instead of a dedicated read + full LDS wait per chunk
# speedup vs baseline: 1.0039x; 1.0012x over previous
;     ...
;             for (int g = 0; g < (act ? 4 : 0); ++g) { float pp[16];
;                 gdn_group8(S, pp, 0, Lc, g * 16, kg, vl); gdn_group8(S, pp, 8, Lc, g * 16 + 8, kg, vl);
;                 Lc[C::OFF_O + (g * 16 + kg) * 32 + vl] = reduce_scatter16(pp, kg); }
.Lgdn_pre_done:
	v_add_u32_e32 v173, 0x200, v173

; #define LAS __attribute__((address_space(3)))
; __device__ __forceinline__ int tidx() { int t = threadIdx.x; asm volatile("" : "+v"(t)); return t; }
;     typedef RecCfg<MIX> C;
;     const int tid = tidx(), s = tid >> 3, c4 = (tid & 7) * 4;
;     const Slot sl = slot_of<SAMPLE>(chunk, s, sg);
;     f32x4 o = *(const LAS f32x4*)(L + C::OFF_O + s * 32 + c4);
;     if constexpr (MIX == 3) o = o + *(const LAS f32x4*)(L + C::OFF_XSD + s * 32 + c4);
;     u32x2 w; w.x = pkh(o[0], o[1]); w.y = pkh(o[2], o[3]);
;     if (c4 < nv) *(u32x2*)(raw + (size_t)sl.row * DM + mixer * 256 + head * 64 + vcol0 + c4) = w;
; }
;     ...
;         for (int c = 0; c < SEQ / 64; ++c) {
;             LAS float* Lc = L + (c & 1) * BUF;
; #pragma unroll 1
;             for (int g = 0; g < (act ? 4 : 0); ++g) { float pp[16];
;                 gdn_group8(S, pp, 0, Lc, g * 16, kg, vl); gdn_group8(S, pp, 8, Lc, g * 16 + 8, kg, vl);
;                 Lc[C::OFF_O + (g * 16 + kg) * 32 + vl] = reduce_scatter16(pp, kg); }
;             if (c + 1 < SEQ / 64) { rec_process<MIX, false>(R, par, l, L + ((c + 1) & 1) * BUF, c + 1, sg, head);
;                 if (c + 2 < SEQ / 64) rec_load<MIX, false>(R, proj, c + 2, sg, head, vcol0);
;                 else if (DO_SAMPLE) rec_load<MIX, true>(R, proj, 0, sg, head, vcol0); }
;             __syncthreads();
;             rec_store_o<MIX, false>(Lc, raw, c, sg, MIX, head, vcol0, nv);
.LBB0_420:
	s_waitcnt lgkmcnt(0)
	s_barrier
	s_lshl_b32 s3, s22, 2
	s_mov_b32 s5, s79
	v_add_u32_e32 v14, s3, v182
	ds_read_b128 v[188:191], v14 offset:50176
	s_cmp_eq_u32 s2, 32
	s_cbranch_scc1 .Lgdn_last_o
	s_mov_b32 s12, s2
	s_bitcmp1_b32 s12, 0
	s_cselect_b32 s22, 0x3900, 0
	s_and_saveexec_b64 s[6:7], s[42:43]
	s_cbranch_execz .Lgdn_o_noloop
	s_lshl_b32 s5, s22, 2
	s_mov_b32 s8, 4
	s_add_i32 s2, s17, s5
	v_add_u32_e32 v172, s5, v26
	v_add_u32_e32 v173, s5, v25
	v_mov_b32_e32 v174, s2
	v_bfrev_b32_e32 v175, v20
	s_movk_i32 s3, 0x4400
	v_lshrrev_b32_e32 v175, 28, v175
	v_lshlrev_b32_e32 v175, 7, v175
	v_add3_u32 v175, v175, v173, s3
	ds_read_b128 v[28:31], v172 offset:0
	ds_read_b128 v[32:35], v172 offset:16384
	ds_read_b128 v[36:39], v172 offset:256
	ds_read_b128 v[40:43], v172 offset:16640
	ds_read_b128 v[44:47], v172 offset:512
	ds_read_b128 v[48:51], v172 offset:16896
	ds_read_b128 v[52:55], v172 offset:768
	ds_read_b128 v[56:59], v172 offset:17152
	ds_read2_b32 v[60:61], v173 offset1:32
	ds_read2_b32 v[62:63], v173 offset0:64 offset1:96
	ds_read2_b64 v[64:67], v174 offset0:0 offset1:2
	ds_read2_b64 v[68:71], v174 offset0:4 offset1:6
	s_waitcnt lgkmcnt(12)
	v_cvt_pk_f16_f32 v188, v188, v189
	v_cvt_pk_f16_f32 v189, v190, v191
	global_store_dwordx2 v[184:185], v[188:189], off offset:512
	v_add_co_u32_e32 v184, vcc, 0x20000, v184
	s_nop 1
	v_addc_co_u32_e32 v185, vcc, 0, v185, vcc
	s_branch .Lgdn_pre_done
.Lgdn_o_noloop:
	s_or_b64 exec, exec, s[6:7]
	s_waitcnt lgkmcnt(0)
	v_cvt_pk_f16_f32 v188, v188, v189
	v_cvt_pk_f16_f32 v189, v190, v191
	global_store_dwordx2 v[184:185], v[188:189], off offset:512
	v_add_co_u32_e32 v184, vcc, 0x20000, v184
	s_nop 1
	v_addc_co_u32_e32 v185, vcc, 0, v185, vcc
	s_branch .LBB0_413
.Lgdn_last_o:
	s_waitcnt lgkmcnt(0)
	v_cvt_pk_f16_f32 v188, v188, v189
	v_cvt_pk_f16_f32 v189, v190, v191
	global_store_dwordx2 v[184:185], v[188:189], off offset:512
	v_add_co_u32_e32 v184, vcc, 0x20000, v184
	s_nop 1
	v_addc_co_u32_e32 v185, vcc, 0, v185, vcc
